# P1 gate-tile epilogue stores tagged nt (gates are consumed only after the attention phase, keep L2/MALL for QKV)
# baseline (speedup 1.0000x reference)
; #define GAS __attribute__((address_space(1)))
; __device__ __forceinline__ unsigned cvt_pk_bf16(float lo, float hi) { f32x2 v = {lo, hi}; bf16x2_t b = __builtin_convertvector(v, bf16x2_t); return __builtin_bit_cast(unsigned, b); }
; __device__ __forceinline__ float sigmoid_f(float x) { return __builtin_amdgcn_rcpf(1.0f + __builtin_amdgcn_exp2f(-x * LOG2E)); }
;     __device__ __forceinline__ void operator()(const f32x4 (&acc)[2][2][4][2], const Unit& u, int wr, int wc, int fr, int fq) const {
;     ...
;         const int c = u.pn - 18, br = c >> 2; GAS bf16_t* G = (br < 2) ? g01 + (size_t)br * MROWS * 1024 : g2;
;         const int row0 = u.pm * BM + wr * 64 + fr; const int col0 = (c & 3) * BM + wc * 32 + 8 * fq;
;         f32x4 bv[2][2];
; #pragma unroll
;         for (int bj = 0; bj < 2; ++bj)
; #pragma unroll
;             for (int n = 0; n < 2; ++n) bv[bj][n] = *(const GAS f32x4*)(bias + br * 1024 + col0 + bj * HALF + 4 * n);
; #pragma unroll
;         for (int ai = 0; ai < 2; ++ai)
; #pragma unroll
;             for (int m = 0; m < 4; ++m) { const int row = row0 + ai * HALF + m * 16; const float rs = q.rs1[row]; GAS bf16_t* rowp = G + (size_t)row * 1024 + col0;
; #pragma unroll
;                 for (int bj = 0; bj < 2; ++bj) { const f32x4 v0 = acc[ai][bj][m][0] * rs + bv[bj][0], v1 = acc[ai][bj][m][1] * rs + bv[bj][1];
;                     u32x4 w; w.x = cvt_pk_bf16(fmaxf(sigmoid_f(v0[0]), 1e-30f), fmaxf(sigmoid_f(v0[1]), 1e-30f)); w.y = cvt_pk_bf16(fmaxf(sigmoid_f(v0[2]), 1e-30f), fmaxf(sigmoid_f(v0[3]), 1e-30f));
;                     w.z = cvt_pk_bf16(fmaxf(sigmoid_f(v1[0]), 1e-30f), fmaxf(sigmoid_f(v1[1]), 1e-30f)); w.w = cvt_pk_bf16(fmaxf(sigmoid_f(v1[2]), 1e-30f), fmaxf(sigmoid_f(v1[3]), 1e-30f));
;                     *(GAS u32x4*)(rowp + bj * HALF) = w; } }
.LBB0_171:
	s_sub_i32 s11, s10, 18
	s_lshr_b32 s13, s11, 2
	s_lshl_b32 s15, s11, 8
	s_lshl_b32 s72, s13, 10
	s_and_b32 s15, s15, 0x300
	s_lshl_b64 s[20:21], s[72:73], 2
	s_add_u32 s20, s48, s20
	s_addc_u32 s21, s49, s21
	s_lshl_b32 s13, s13, 26
	s_add_u32 s13, s31, s13
	v_or_b32_e32 v0, s15, v203
	s_addc_u32 s15, s30, 0
	v_lshlrev_b32_e32 v134, 2, v0
	s_cmp_lt_u32 s11, 8
	v_ashrrev_i32_e32 v163, 31, v162
	global_load_dwordx4 v[138:141], v134, s[20:21] offset:16
	global_load_dwordx4 v[142:145], v134, s[20:21]
	global_load_dwordx4 v[130:133], v134, s[20:21] offset:528
	s_nop 0
	global_load_dwordx4 v[134:137], v134, s[20:21] offset:512
	s_cselect_b32 s21, s15, s47
	s_cselect_b32 s20, s13, s46
	v_lshlrev_b32_e32 v0, 1, v0
	v_lshl_add_u64 v[192:193], v[162:163], 2, s[2:3]
	v_lshl_add_u64 v[194:195], s[20:21], 0, v[0:1]
	global_load_dword v206, v[192:193], off
	global_load_dword v207, v[192:193], off offset:64
	global_load_dword v208, v[192:193], off offset:128
	global_load_dword v209, v[192:193], off offset:192
	global_load_dword v210, v[192:193], off offset:512
	global_load_dword v211, v[192:193], off offset:576
	global_load_dword v212, v[192:193], off offset:640
	global_load_dword v213, v[192:193], off offset:704
	v_lshlrev_b64 v[146:147], 11, v[162:163]
	v_lshl_add_u64 v[164:165], v[194:195], 0, v[146:147]
	s_mov_b32 s11, 0x40000
	s_mov_b64 s[20:21], 0x40000
	s_waitcnt vmcnt(0)
	s_nop 1
	v_mov_b32_e32 v0, v206
	v_pk_fma_f32 v[146:147], v[126:127], v[0:1], v[142:143] op_sel_hi:[1,0,1]
	s_nop 0
	v_mul_f32_e32 v146, 0xbfb8aa3b, v146
	v_mul_f32_e32 v147, 0xbfb8aa3b, v147
	v_exp_f32_e32 v146, v146
	v_exp_f32_e32 v147, v147
	v_pk_fma_f32 v[148:149], v[128:129], v[0:1], v[144:145] op_sel_hi:[1,0,1]
	v_pk_fma_f32 v[198:199], v[122:123], v[0:1], v[138:139] op_sel_hi:[1,0,1]
	v_add_f32_e32 v146, 1.0, v146
	v_add_f32_e32 v147, 1.0, v147
	v_rcp_f32_e32 v146, v146
	v_rcp_f32_e32 v147, v147
	v_pk_fma_f32 v[196:197], v[124:125], v[0:1], v[140:141] op_sel_hi:[1,0,1]
	v_max_f32_e32 v146, 0xda24260, v146
	v_max_f32_e32 v147, 0xda24260, v147
	v_cvt_pk_bf16_f32 v146, v146, v147
	v_mul_f32_e32 v147, 0xbfb8aa3b, v148
	v_mul_f32_e32 v148, 0xbfb8aa3b, v149
	v_exp_f32_e32 v147, v147
	v_exp_f32_e32 v148, v148
	v_mul_f32_e32 v149, 0xbfb8aa3b, v199
	v_exp_f32_e32 v149, v149
	v_add_f32_e32 v147, 1.0, v147
	v_add_f32_e32 v148, 1.0, v148
	v_rcp_f32_e32 v147, v147
	v_rcp_f32_e32 v148, v148
	v_add_f32_e32 v149, 1.0, v149
	v_rcp_f32_e32 v149, v149
	v_max_f32_e32 v147, 0xda24260, v147
	v_max_f32_e32 v148, 0xda24260, v148
	v_cvt_pk_bf16_f32 v147, v147, v148
	v_mul_f32_e32 v148, 0xbfb8aa3b, v198
	v_exp_f32_e32 v148, v148
	v_max_f32_e32 v149, 0xda24260, v149
	v_mul_f32_e32 v163, 0xbfb8aa3b, v197
	v_exp_f32_e32 v163, v163
	v_add_f32_e32 v148, 1.0, v148
	v_rcp_f32_e32 v148, v148
	v_pk_fma_f32 v[198:199], v[120:121], v[0:1], v[136:137] op_sel_hi:[1,0,1]
	v_add_f32_e32 v163, 1.0, v163
	v_rcp_f32_e32 v163, v163
	v_max_f32_e32 v148, 0xda24260, v148
	v_cvt_pk_bf16_f32 v148, v148, v149
	v_mul_f32_e32 v149, 0xbfb8aa3b, v196
	v_exp_f32_e32 v149, v149
	v_max_f32_e32 v163, 0xda24260, v163
	v_pk_fma_f32 v[196:197], v[116:117], v[0:1], v[132:133] op_sel_hi:[1,0,1]
	v_add_f32_e32 v149, 1.0, v149
	v_rcp_f32_e32 v149, v149
	s_nop 0
	v_max_f32_e32 v149, 0xda24260, v149
	v_cvt_pk_bf16_f32 v149, v149, v163
	global_store_dwordx4 v[164:165], v[146:149], off nt
	s_nop 1
	v_pk_fma_f32 v[146:147], v[118:119], v[0:1], v[134:135] op_sel_hi:[1,0,1]
	v_pk_fma_f32 v[148:149], v[114:115], v[0:1], v[130:131] op_sel_hi:[1,0,1]
	v_mul_f32_e32 v0, 0xbfb8aa3b, v146
	v_mul_f32_e32 v146, 0xbfb8aa3b, v147
	v_exp_f32_e32 v0, v0
	v_exp_f32_e32 v146, v146
	v_mul_f32_e32 v147, 0xbfb8aa3b, v199
	v_exp_f32_e32 v147, v147
	v_add_f32_e32 v0, 1.0, v0
	v_add_f32_e32 v146, 1.0, v146
	v_rcp_f32_e32 v0, v0
	v_rcp_f32_e32 v146, v146
	v_add_f32_e32 v147, 1.0, v147
	v_rcp_f32_e32 v147, v147
	v_max_f32_e32 v0, 0xda24260, v0
	v_max_f32_e32 v146, 0xda24260, v146
	v_cvt_pk_bf16_f32 v146, v0, v146
	v_mul_f32_e32 v0, 0xbfb8aa3b, v198
	v_exp_f32_e32 v0, v0
	v_max_f32_e32 v147, 0xda24260, v147
	v_add_f32_e32 v0, 1.0, v0
	v_rcp_f32_e32 v0, v0
	s_nop 0
	v_max_f32_e32 v0, 0xda24260, v0
	v_cvt_pk_bf16_f32 v147, v0, v147
	v_mul_f32_e32 v0, 0xbfb8aa3b, v148
	v_mul_f32_e32 v148, 0xbfb8aa3b, v149
	v_exp_f32_e32 v0, v0
	v_exp_f32_e32 v148, v148
	v_mul_f32_e32 v149, 0xbfb8aa3b, v197
	v_exp_f32_e32 v149, v149
	v_add_f32_e32 v0, 1.0, v0
	v_add_f32_e32 v148, 1.0, v148
	v_rcp_f32_e32 v0, v0
	v_rcp_f32_e32 v148, v148
	v_add_f32_e32 v149, 1.0, v149
	v_rcp_f32_e32 v149, v149
	v_max_f32_e32 v0, 0xda24260, v0
	v_max_f32_e32 v148, 0xda24260, v148
	v_cvt_pk_bf16_f32 v148, v0, v148
	v_mul_f32_e32 v0, 0xbfb8aa3b, v196
	v_exp_f32_e32 v0, v0
	v_max_f32_e32 v149, 0xda24260, v149
	v_add_f32_e32 v0, 1.0, v0
	v_rcp_f32_e32 v0, v0
	s_nop 0
	v_max_f32_e32 v0, 0xda24260, v0
	v_cvt_pk_bf16_f32 v149, v0, v149
	global_store_dwordx4 v[164:165], v[146:149], off offset:256 nt
	s_nop 1
	v_or_b32_e32 v146, 16, v162
	v_ashrrev_i32_e32 v147, 31, v146
	v_lshl_add_u64 v[148:149], v[146:147], 2, s[2:3]
	v_lshlrev_b64 v[146:147], 11, v[146:147]
	v_lshl_add_u64 v[196:197], v[194:195], 0, v[146:147]
	s_nop 1
	v_mov_b32_e32 v0, v207
	v_pk_fma_f32 v[146:147], v[110:111], v[0:1], v[142:143] op_sel_hi:[1,0,1]
	s_nop 0
	v_mul_f32_e32 v146, 0xbfb8aa3b, v146
	v_mul_f32_e32 v147, 0xbfb8aa3b, v147
	v_exp_f32_e32 v146, v146
	v_exp_f32_e32 v147, v147
	v_pk_fma_f32 v[148:149], v[112:113], v[0:1], v[144:145] op_sel_hi:[1,0,1]
	v_pk_fma_f32 v[200:201], v[106:107], v[0:1], v[138:139] op_sel_hi:[1,0,1]
	v_add_f32_e32 v146, 1.0, v146
	v_add_f32_e32 v147, 1.0, v147
	v_rcp_f32_e32 v146, v146
; #define GAS __attribute__((address_space(1)))
; __device__ __forceinline__ unsigned cvt_pk_bf16(float lo, float hi) { f32x2 v = {lo, hi}; bf16x2_t b = __builtin_convertvector(v, bf16x2_t); return __builtin_bit_cast(unsigned, b); }
; __device__ __forceinline__ float sigmoid_f(float x) { return __builtin_amdgcn_rcpf(1.0f + __builtin_amdgcn_exp2f(-x * LOG2E)); }
;     __device__ __forceinline__ void operator()(const f32x4 (&acc)[2][2][4][2], const Unit& u, int wr, int wc, int fr, int fq) const {
;     ...
;             for (int m = 0; m < 4; ++m) { const int row = row0 + ai * HALF + m * 16; const float rs = q.rs1[row]; GAS bf16_t* rowp = G + (size_t)row * 1024 + col0;
; #pragma unroll
;                 for (int bj = 0; bj < 2; ++bj) { const f32x4 v0 = acc[ai][bj][m][0] * rs + bv[bj][0], v1 = acc[ai][bj][m][1] * rs + bv[bj][1];
;                     u32x4 w; w.x = cvt_pk_bf16(fmaxf(sigmoid_f(v0[0]), 1e-30f), fmaxf(sigmoid_f(v0[1]), 1e-30f)); w.y = cvt_pk_bf16(fmaxf(sigmoid_f(v0[2]), 1e-30f), fmaxf(sigmoid_f(v0[3]), 1e-30f));
;                     w.z = cvt_pk_bf16(fmaxf(sigmoid_f(v1[0]), 1e-30f), fmaxf(sigmoid_f(v1[1]), 1e-30f)); w.w = cvt_pk_bf16(fmaxf(sigmoid_f(v1[2]), 1e-30f), fmaxf(sigmoid_f(v1[3]), 1e-30f));
;                     *(GAS u32x4*)(rowp + bj * HALF) = w; } }
	v_rcp_f32_e32 v147, v147
	v_pk_fma_f32 v[198:199], v[108:109], v[0:1], v[140:141] op_sel_hi:[1,0,1]
	v_max_f32_e32 v146, 0xda24260, v146
	v_max_f32_e32 v147, 0xda24260, v147
	v_cvt_pk_bf16_f32 v146, v146, v147
	v_mul_f32_e32 v147, 0xbfb8aa3b, v148
	v_mul_f32_e32 v148, 0xbfb8aa3b, v149
	v_exp_f32_e32 v147, v147
	v_exp_f32_e32 v148, v148
	v_mul_f32_e32 v149, 0xbfb8aa3b, v201
	v_exp_f32_e32 v149, v149
	v_add_f32_e32 v147, 1.0, v147
	v_add_f32_e32 v148, 1.0, v148
	v_rcp_f32_e32 v147, v147
	v_rcp_f32_e32 v148, v148
	v_add_f32_e32 v149, 1.0, v149
	v_rcp_f32_e32 v149, v149
	v_max_f32_e32 v147, 0xda24260, v147
	v_max_f32_e32 v148, 0xda24260, v148
	v_cvt_pk_bf16_f32 v147, v147, v148
	v_mul_f32_e32 v148, 0xbfb8aa3b, v200
	v_exp_f32_e32 v148, v148
	v_max_f32_e32 v149, 0xda24260, v149
	v_mul_f32_e32 v163, 0xbfb8aa3b, v199
	v_exp_f32_e32 v163, v163
	v_add_f32_e32 v148, 1.0, v148
	v_rcp_f32_e32 v148, v148
	v_pk_fma_f32 v[200:201], v[104:105], v[0:1], v[136:137] op_sel_hi:[1,0,1]
	v_add_f32_e32 v163, 1.0, v163
	v_rcp_f32_e32 v163, v163
	v_max_f32_e32 v148, 0xda24260, v148
	v_cvt_pk_bf16_f32 v148, v148, v149
	v_mul_f32_e32 v149, 0xbfb8aa3b, v198
	v_exp_f32_e32 v149, v149
	v_max_f32_e32 v163, 0xda24260, v163
	v_pk_fma_f32 v[198:199], v[100:101], v[0:1], v[132:133] op_sel_hi:[1,0,1]
	v_add_f32_e32 v149, 1.0, v149
	v_rcp_f32_e32 v149, v149
	s_nop 0
	v_max_f32_e32 v149, 0xda24260, v149
	v_cvt_pk_bf16_f32 v149, v149, v163
	global_store_dwordx4 v[196:197], v[146:149], off nt
	s_nop 1
	v_pk_fma_f32 v[146:147], v[102:103], v[0:1], v[134:135] op_sel_hi:[1,0,1]
	v_pk_fma_f32 v[148:149], v[98:99], v[0:1], v[130:131] op_sel_hi:[1,0,1]
	v_mul_f32_e32 v0, 0xbfb8aa3b, v146
	v_mul_f32_e32 v146, 0xbfb8aa3b, v147
	v_exp_f32_e32 v0, v0
	v_exp_f32_e32 v146, v146
	v_mul_f32_e32 v147, 0xbfb8aa3b, v201
	v_exp_f32_e32 v147, v147
	v_add_f32_e32 v0, 1.0, v0
	v_add_f32_e32 v146, 1.0, v146
	v_rcp_f32_e32 v0, v0
	v_rcp_f32_e32 v146, v146
	v_add_f32_e32 v147, 1.0, v147
	v_rcp_f32_e32 v147, v147
	v_max_f32_e32 v0, 0xda24260, v0
	v_max_f32_e32 v146, 0xda24260, v146
	v_cvt_pk_bf16_f32 v146, v0, v146
	v_mul_f32_e32 v0, 0xbfb8aa3b, v200
	v_exp_f32_e32 v0, v0
	v_max_f32_e32 v147, 0xda24260, v147
	v_add_f32_e32 v0, 1.0, v0
	v_rcp_f32_e32 v0, v0
	s_nop 0
	v_max_f32_e32 v0, 0xda24260, v0
	v_cvt_pk_bf16_f32 v147, v0, v147
	v_mul_f32_e32 v0, 0xbfb8aa3b, v148
	v_mul_f32_e32 v148, 0xbfb8aa3b, v149
	v_exp_f32_e32 v0, v0
	v_exp_f32_e32 v148, v148
	v_mul_f32_e32 v149, 0xbfb8aa3b, v199
	v_exp_f32_e32 v149, v149
	v_add_f32_e32 v0, 1.0, v0
	v_add_f32_e32 v148, 1.0, v148
	v_rcp_f32_e32 v0, v0
	v_rcp_f32_e32 v148, v148
	v_add_f32_e32 v149, 1.0, v149
	v_rcp_f32_e32 v149, v149
	v_max_f32_e32 v0, 0xda24260, v0
	v_max_f32_e32 v148, 0xda24260, v148
	v_cvt_pk_bf16_f32 v148, v0, v148
	v_mul_f32_e32 v0, 0xbfb8aa3b, v198
	v_exp_f32_e32 v0, v0
	v_max_f32_e32 v149, 0xda24260, v149
	v_add_f32_e32 v0, 1.0, v0
	v_rcp_f32_e32 v0, v0
	s_nop 0
	v_max_f32_e32 v0, 0xda24260, v0
	v_cvt_pk_bf16_f32 v149, v0, v149
	global_store_dwordx4 v[196:197], v[146:149], off offset:256 nt
	s_nop 1
	v_or_b32_e32 v146, 32, v162
	v_ashrrev_i32_e32 v147, 31, v146
	v_lshl_add_u64 v[148:149], v[146:147], 2, s[2:3]
	v_lshlrev_b64 v[146:147], 11, v[146:147]
	v_lshl_add_u64 v[146:147], v[194:195], 0, v[146:147]
	s_nop 1
	v_mov_b32_e32 v0, v208
	v_pk_fma_f32 v[148:149], v[96:97], v[0:1], v[144:145] op_sel_hi:[1,0,1]
	s_nop 0
	v_mul_f32_e32 v148, 0xbfb8aa3b, v148
	v_mul_f32_e32 v149, 0xbfb8aa3b, v149
	v_exp_f32_e32 v148, v148
	v_exp_f32_e32 v149, v149
	v_pk_fma_f32 v[196:197], v[94:95], v[0:1], v[142:143] op_sel_hi:[1,0,1]
	v_pk_fma_f32 v[198:199], v[90:91], v[0:1], v[138:139] op_sel_hi:[1,0,1]
	v_add_f32_e32 v148, 1.0, v148
	v_add_f32_e32 v149, 1.0, v149
	v_rcp_f32_e32 v148, v148
	v_rcp_f32_e32 v149, v149
	v_mul_f32_e32 v163, 0xbfb8aa3b, v196
	v_mul_f32_e32 v196, 0xbfb8aa3b, v197
	v_max_f32_e32 v148, 0xda24260, v148
	v_max_f32_e32 v149, 0xda24260, v149
	v_cvt_pk_bf16_f32 v197, v148, v149
	v_mul_f32_e32 v148, 0xbfb8aa3b, v198
	v_mul_f32_e32 v149, 0xbfb8aa3b, v199
	v_exp_f32_e32 v148, v148
	v_exp_f32_e32 v149, v149
	v_pk_fma_f32 v[200:201], v[92:93], v[0:1], v[140:141] op_sel_hi:[1,0,1]
	v_exp_f32_e32 v163, v163
	v_add_f32_e32 v148, 1.0, v148
	v_add_f32_e32 v149, 1.0, v149
	v_rcp_f32_e32 v148, v148
	v_rcp_f32_e32 v149, v149
	v_exp_f32_e32 v196, v196
	v_add_f32_e32 v163, 1.0, v163
	v_max_f32_e32 v148, 0xda24260, v148
	v_max_f32_e32 v149, 0xda24260, v149
	v_cvt_pk_bf16_f32 v198, v148, v149
	v_mul_f32_e32 v148, 0xbfb8aa3b, v200
	v_mul_f32_e32 v149, 0xbfb8aa3b, v201
	v_exp_f32_e32 v148, v148
	v_exp_f32_e32 v149, v149
	v_add_f32_e32 v196, 1.0, v196
	v_rcp_f32_e32 v163, v163
	v_add_f32_e32 v148, 1.0, v148
	v_add_f32_e32 v149, 1.0, v149
	v_rcp_f32_e32 v196, v196
	v_rcp_f32_e32 v148, v148
	v_rcp_f32_e32 v149, v149
	v_max_f32_e32 v163, 0xda24260, v163
	v_max_f32_e32 v196, 0xda24260, v196
	v_max_f32_e32 v148, 0xda24260, v148
	v_max_f32_e32 v149, 0xda24260, v149
	v_cvt_pk_bf16_f32 v196, v163, v196
	v_cvt_pk_bf16_f32 v199, v148, v149
	global_store_dwordx4 v[146:147], v[196:199], off nt
	v_pk_fma_f32 v[200:201], v[88:89], v[0:1], v[136:137] op_sel_hi:[1,0,1]
	v_pk_fma_f32 v[148:149], v[84:85], v[0:1], v[132:133] op_sel_hi:[1,0,1]
	v_pk_fma_f32 v[198:199], v[86:87], v[0:1], v[134:135] op_sel_hi:[1,0,1]
	v_pk_fma_f32 v[196:197], v[82:83], v[0:1], v[130:131] op_sel_hi:[1,0,1]
	v_mul_f32_e32 v0, 0xbfb8aa3b, v198
	v_mul_f32_e32 v163, 0xbfb8aa3b, v199
	v_exp_f32_e32 v0, v0
	v_exp_f32_e32 v163, v163
	v_add_f32_e32 v0, 1.0, v0
	v_add_f32_e32 v163, 1.0, v163
	v_rcp_f32_e32 v0, v0
	v_rcp_f32_e32 v163, v163
	v_max_f32_e32 v0, 0xda24260, v0
	v_max_f32_e32 v163, 0xda24260, v163
; #define GAS __attribute__((address_space(1)))
; __device__ __forceinline__ unsigned cvt_pk_bf16(float lo, float hi) { f32x2 v = {lo, hi}; bf16x2_t b = __builtin_convertvector(v, bf16x2_t); return __builtin_bit_cast(unsigned, b); }
; __device__ __forceinline__ float sigmoid_f(float x) { return __builtin_amdgcn_rcpf(1.0f + __builtin_amdgcn_exp2f(-x * LOG2E)); }
;     __device__ __forceinline__ void operator()(const f32x4 (&acc)[2][2][4][2], const Unit& u, int wr, int wc, int fr, int fq) const {
;     ...
;             for (int m = 0; m < 4; ++m) { const int row = row0 + ai * HALF + m * 16; const float rs = q.rs1[row]; GAS bf16_t* rowp = G + (size_t)row * 1024 + col0;
; #pragma unroll
;                 for (int bj = 0; bj < 2; ++bj) { const f32x4 v0 = acc[ai][bj][m][0] * rs + bv[bj][0], v1 = acc[ai][bj][m][1] * rs + bv[bj][1];
;                     u32x4 w; w.x = cvt_pk_bf16(fmaxf(sigmoid_f(v0[0]), 1e-30f), fmaxf(sigmoid_f(v0[1]), 1e-30f)); w.y = cvt_pk_bf16(fmaxf(sigmoid_f(v0[2]), 1e-30f), fmaxf(sigmoid_f(v0[3]), 1e-30f));
;                     w.z = cvt_pk_bf16(fmaxf(sigmoid_f(v1[0]), 1e-30f), fmaxf(sigmoid_f(v1[1]), 1e-30f)); w.w = cvt_pk_bf16(fmaxf(sigmoid_f(v1[2]), 1e-30f), fmaxf(sigmoid_f(v1[3]), 1e-30f));
;                     *(GAS u32x4*)(rowp + bj * HALF) = w; } }
	v_cvt_pk_bf16_f32 v198, v0, v163
	v_mul_f32_e32 v0, 0xbfb8aa3b, v200
	v_mul_f32_e32 v163, 0xbfb8aa3b, v201
	v_exp_f32_e32 v0, v0
	v_exp_f32_e32 v163, v163
	v_add_f32_e32 v0, 1.0, v0
	v_add_f32_e32 v163, 1.0, v163
	v_rcp_f32_e32 v0, v0
	v_rcp_f32_e32 v163, v163
	v_max_f32_e32 v0, 0xda24260, v0
	v_max_f32_e32 v163, 0xda24260, v163
	v_cvt_pk_bf16_f32 v199, v0, v163
	v_mul_f32_e32 v0, 0xbfb8aa3b, v196
	v_mul_f32_e32 v163, 0xbfb8aa3b, v197
	v_exp_f32_e32 v0, v0
	v_exp_f32_e32 v163, v163
	v_add_f32_e32 v0, 1.0, v0
	v_add_f32_e32 v163, 1.0, v163
	v_rcp_f32_e32 v0, v0
	v_rcp_f32_e32 v163, v163
	v_max_f32_e32 v0, 0xda24260, v0
	v_max_f32_e32 v163, 0xda24260, v163
	v_cvt_pk_bf16_f32 v200, v0, v163
	v_mul_f32_e32 v0, 0xbfb8aa3b, v148
	v_mul_f32_e32 v148, 0xbfb8aa3b, v149
	v_exp_f32_e32 v0, v0
	v_exp_f32_e32 v148, v148
	v_add_f32_e32 v0, 1.0, v0
	v_add_f32_e32 v148, 1.0, v148
	v_rcp_f32_e32 v0, v0
	v_rcp_f32_e32 v148, v148
	v_max_f32_e32 v0, 0xda24260, v0
	v_max_f32_e32 v148, 0xda24260, v148
	v_cvt_pk_bf16_f32 v201, v0, v148
	global_store_dwordx4 v[146:147], v[198:201], off offset:256 nt
	v_or_b32_e32 v146, 48, v162
	v_ashrrev_i32_e32 v147, 31, v146
	v_lshl_add_u64 v[148:149], v[146:147], 2, s[2:3]
	v_lshlrev_b64 v[146:147], 11, v[146:147]
	v_lshl_add_u64 v[194:195], v[194:195], 0, v[146:147]
	s_nop 1
	v_mov_b32_e32 v0, v209
	v_pk_fma_f32 v[146:147], v[78:79], v[0:1], v[142:143] op_sel_hi:[1,0,1]
	s_nop 0
	v_mul_f32_e32 v146, 0xbfb8aa3b, v146
	v_mul_f32_e32 v147, 0xbfb8aa3b, v147
	v_exp_f32_e32 v146, v146
	v_exp_f32_e32 v147, v147
	v_pk_fma_f32 v[148:149], v[80:81], v[0:1], v[144:145] op_sel_hi:[1,0,1]
	v_pk_fma_f32 v[198:199], v[74:75], v[0:1], v[138:139] op_sel_hi:[1,0,1]
	v_add_f32_e32 v146, 1.0, v146
	v_add_f32_e32 v147, 1.0, v147
	v_rcp_f32_e32 v146, v146
	v_rcp_f32_e32 v147, v147
	v_pk_fma_f32 v[196:197], v[76:77], v[0:1], v[140:141] op_sel_hi:[1,0,1]
	v_max_f32_e32 v146, 0xda24260, v146
	v_max_f32_e32 v147, 0xda24260, v147
	v_cvt_pk_bf16_f32 v146, v146, v147
	v_mul_f32_e32 v147, 0xbfb8aa3b, v148
	v_mul_f32_e32 v148, 0xbfb8aa3b, v149
	v_exp_f32_e32 v147, v147
	v_exp_f32_e32 v148, v148
	v_mul_f32_e32 v149, 0xbfb8aa3b, v199
	v_exp_f32_e32 v149, v149
	v_add_f32_e32 v147, 1.0, v147
	v_add_f32_e32 v148, 1.0, v148
	v_rcp_f32_e32 v147, v147
	v_rcp_f32_e32 v148, v148
	v_add_f32_e32 v149, 1.0, v149
	v_rcp_f32_e32 v149, v149
	v_max_f32_e32 v147, 0xda24260, v147
	v_max_f32_e32 v148, 0xda24260, v148
	v_cvt_pk_bf16_f32 v147, v147, v148
	v_mul_f32_e32 v148, 0xbfb8aa3b, v198
	v_exp_f32_e32 v148, v148
	v_max_f32_e32 v149, 0xda24260, v149
	v_mul_f32_e32 v163, 0xbfb8aa3b, v197
	v_exp_f32_e32 v163, v163
	v_add_f32_e32 v148, 1.0, v148
	v_rcp_f32_e32 v148, v148
	v_pk_fma_f32 v[198:199], v[66:67], v[0:1], v[130:131] op_sel_hi:[1,0,1]
	v_add_f32_e32 v163, 1.0, v163
	v_rcp_f32_e32 v163, v163
	v_max_f32_e32 v148, 0xda24260, v148
	v_cvt_pk_bf16_f32 v148, v148, v149
	v_mul_f32_e32 v149, 0xbfb8aa3b, v196
	v_exp_f32_e32 v149, v149
	v_max_f32_e32 v163, 0xda24260, v163
	v_pk_fma_f32 v[196:197], v[68:69], v[0:1], v[132:133] op_sel_hi:[1,0,1]
	v_add_f32_e32 v149, 1.0, v149
	v_rcp_f32_e32 v149, v149
	s_nop 0
	v_max_f32_e32 v149, 0xda24260, v149
	v_cvt_pk_bf16_f32 v149, v149, v163
	global_store_dwordx4 v[194:195], v[146:149], off nt
	s_nop 1
	v_pk_fma_f32 v[146:147], v[70:71], v[0:1], v[134:135] op_sel_hi:[1,0,1]
	v_pk_fma_f32 v[148:149], v[72:73], v[0:1], v[136:137] op_sel_hi:[1,0,1]
	v_mul_f32_e32 v0, 0xbfb8aa3b, v146
	v_mul_f32_e32 v146, 0xbfb8aa3b, v147
	v_exp_f32_e32 v0, v0
	v_exp_f32_e32 v146, v146
	v_mul_f32_e32 v147, 0xbfb8aa3b, v149
	v_exp_f32_e32 v147, v147
	v_add_f32_e32 v0, 1.0, v0
	v_add_f32_e32 v146, 1.0, v146
	v_rcp_f32_e32 v0, v0
	v_rcp_f32_e32 v146, v146
	v_add_f32_e32 v147, 1.0, v147
	v_rcp_f32_e32 v147, v147
	v_max_f32_e32 v0, 0xda24260, v0
	v_max_f32_e32 v146, 0xda24260, v146
	v_cvt_pk_bf16_f32 v146, v0, v146
	v_mul_f32_e32 v0, 0xbfb8aa3b, v148
	v_exp_f32_e32 v0, v0
	v_max_f32_e32 v147, 0xda24260, v147
	v_mul_f32_e32 v148, 0xbfb8aa3b, v199
	v_exp_f32_e32 v148, v148
	v_add_f32_e32 v0, 1.0, v0
	v_rcp_f32_e32 v0, v0
	v_mul_f32_e32 v149, 0xbfb8aa3b, v197
	v_add_f32_e32 v148, 1.0, v148
	v_rcp_f32_e32 v148, v148
	v_max_f32_e32 v0, 0xda24260, v0
	v_cvt_pk_bf16_f32 v147, v0, v147
	v_mul_f32_e32 v0, 0xbfb8aa3b, v198
	v_exp_f32_e32 v0, v0
	v_max_f32_e32 v148, 0xda24260, v148
	v_exp_f32_e32 v149, v149
	v_add_f32_e32 v0, 1.0, v0
	v_rcp_f32_e32 v0, v0
	v_add_f32_e32 v149, 1.0, v149
	v_rcp_f32_e32 v149, v149
	v_max_f32_e32 v0, 0xda24260, v0
	v_cvt_pk_bf16_f32 v148, v0, v148
	v_mul_f32_e32 v0, 0xbfb8aa3b, v196
	v_exp_f32_e32 v0, v0
	v_max_f32_e32 v149, 0xda24260, v149
	v_add_f32_e32 v0, 1.0, v0
	v_rcp_f32_e32 v0, v0
	s_nop 0
	v_max_f32_e32 v0, 0xda24260, v0
	v_cvt_pk_bf16_f32 v149, v0, v149
	global_store_dwordx4 v[194:195], v[146:149], off offset:256 nt
	v_lshl_add_u64 v[194:195], v[164:165], 0, s[20:21]
	s_mov_b64 s[20:21], 0x48000
	s_nop 1
	v_mov_b32_e32 v0, v210
	v_pk_fma_f32 v[146:147], v[62:63], v[0:1], v[142:143] op_sel_hi:[1,0,1]
	s_nop 0
	v_mul_f32_e32 v146, 0xbfb8aa3b, v146
	v_mul_f32_e32 v147, 0xbfb8aa3b, v147
	v_exp_f32_e32 v146, v146
	v_exp_f32_e32 v147, v147
	v_pk_fma_f32 v[148:149], v[64:65], v[0:1], v[144:145] op_sel_hi:[1,0,1]
	v_pk_fma_f32 v[198:199], v[58:59], v[0:1], v[138:139] op_sel_hi:[1,0,1]
	v_add_f32_e32 v146, 1.0, v146
	v_add_f32_e32 v147, 1.0, v147
	v_rcp_f32_e32 v146, v146
	v_rcp_f32_e32 v147, v147
	v_pk_fma_f32 v[196:197], v[60:61], v[0:1], v[140:141] op_sel_hi:[1,0,1]
	v_max_f32_e32 v146, 0xda24260, v146
	v_max_f32_e32 v147, 0xda24260, v147
	v_cvt_pk_bf16_f32 v146, v146, v147
	v_mul_f32_e32 v147, 0xbfb8aa3b, v148
	v_mul_f32_e32 v148, 0xbfb8aa3b, v149
; #define GAS __attribute__((address_space(1)))
; __device__ __forceinline__ unsigned cvt_pk_bf16(float lo, float hi) { f32x2 v = {lo, hi}; bf16x2_t b = __builtin_convertvector(v, bf16x2_t); return __builtin_bit_cast(unsigned, b); }
; __device__ __forceinline__ float sigmoid_f(float x) { return __builtin_amdgcn_rcpf(1.0f + __builtin_amdgcn_exp2f(-x * LOG2E)); }
;     __device__ __forceinline__ void operator()(const f32x4 (&acc)[2][2][4][2], const Unit& u, int wr, int wc, int fr, int fq) const {
;     ...
;             for (int m = 0; m < 4; ++m) { const int row = row0 + ai * HALF + m * 16; const float rs = q.rs1[row]; GAS bf16_t* rowp = G + (size_t)row * 1024 + col0;
; #pragma unroll
;                 for (int bj = 0; bj < 2; ++bj) { const f32x4 v0 = acc[ai][bj][m][0] * rs + bv[bj][0], v1 = acc[ai][bj][m][1] * rs + bv[bj][1];
;                     u32x4 w; w.x = cvt_pk_bf16(fmaxf(sigmoid_f(v0[0]), 1e-30f), fmaxf(sigmoid_f(v0[1]), 1e-30f)); w.y = cvt_pk_bf16(fmaxf(sigmoid_f(v0[2]), 1e-30f), fmaxf(sigmoid_f(v0[3]), 1e-30f));
;                     w.z = cvt_pk_bf16(fmaxf(sigmoid_f(v1[0]), 1e-30f), fmaxf(sigmoid_f(v1[1]), 1e-30f)); w.w = cvt_pk_bf16(fmaxf(sigmoid_f(v1[2]), 1e-30f), fmaxf(sigmoid_f(v1[3]), 1e-30f));
;                     *(GAS u32x4*)(rowp + bj * HALF) = w; } }
	v_exp_f32_e32 v147, v147
	v_exp_f32_e32 v148, v148
	v_mul_f32_e32 v149, 0xbfb8aa3b, v199
	v_exp_f32_e32 v149, v149
	v_add_f32_e32 v147, 1.0, v147
	v_add_f32_e32 v148, 1.0, v148
	v_rcp_f32_e32 v147, v147
	v_rcp_f32_e32 v148, v148
	v_add_f32_e32 v149, 1.0, v149
	v_rcp_f32_e32 v149, v149
	v_max_f32_e32 v147, 0xda24260, v147
	v_max_f32_e32 v148, 0xda24260, v148
	v_cvt_pk_bf16_f32 v147, v147, v148
	v_mul_f32_e32 v148, 0xbfb8aa3b, v198
	v_exp_f32_e32 v148, v148
	v_max_f32_e32 v149, 0xda24260, v149
	v_mul_f32_e32 v163, 0xbfb8aa3b, v197
	v_exp_f32_e32 v163, v163
	v_add_f32_e32 v148, 1.0, v148
	v_rcp_f32_e32 v148, v148
	v_pk_fma_f32 v[198:199], v[50:51], v[0:1], v[130:131] op_sel_hi:[1,0,1]
	v_add_f32_e32 v163, 1.0, v163
	v_rcp_f32_e32 v163, v163
	v_max_f32_e32 v148, 0xda24260, v148
	v_cvt_pk_bf16_f32 v148, v148, v149
	v_mul_f32_e32 v149, 0xbfb8aa3b, v196
	v_exp_f32_e32 v149, v149
	v_max_f32_e32 v163, 0xda24260, v163
	v_add_co_u32_e32 v196, vcc, s11, v164
	v_add_f32_e32 v149, 1.0, v149
	v_rcp_f32_e32 v149, v149
	v_addc_co_u32_e32 v197, vcc, 0, v165, vcc
	s_mov_b32 s11, 0x48000
	v_max_f32_e32 v149, 0xda24260, v149
	v_cvt_pk_bf16_f32 v149, v149, v163
	global_store_dwordx4 v[196:197], v[146:149], off nt
	v_pk_fma_f32 v[196:197], v[52:53], v[0:1], v[132:133] op_sel_hi:[1,0,1]
	s_nop 0
	v_pk_fma_f32 v[146:147], v[54:55], v[0:1], v[134:135] op_sel_hi:[1,0,1]
	v_pk_fma_f32 v[148:149], v[56:57], v[0:1], v[136:137] op_sel_hi:[1,0,1]
	v_mul_f32_e32 v0, 0xbfb8aa3b, v146
	v_mul_f32_e32 v146, 0xbfb8aa3b, v147
	v_exp_f32_e32 v0, v0
	v_exp_f32_e32 v146, v146
	v_mul_f32_e32 v147, 0xbfb8aa3b, v149
	v_exp_f32_e32 v147, v147
	v_add_f32_e32 v0, 1.0, v0
	v_add_f32_e32 v146, 1.0, v146
	v_rcp_f32_e32 v0, v0
	v_rcp_f32_e32 v146, v146
	v_add_f32_e32 v147, 1.0, v147
	v_rcp_f32_e32 v147, v147
	v_max_f32_e32 v0, 0xda24260, v0
	v_max_f32_e32 v146, 0xda24260, v146
	v_cvt_pk_bf16_f32 v146, v0, v146
	v_mul_f32_e32 v0, 0xbfb8aa3b, v148
	v_exp_f32_e32 v0, v0
	v_max_f32_e32 v147, 0xda24260, v147
	v_mul_f32_e32 v148, 0xbfb8aa3b, v199
	v_exp_f32_e32 v148, v148
	v_add_f32_e32 v0, 1.0, v0
	v_rcp_f32_e32 v0, v0
	v_mul_f32_e32 v149, 0xbfb8aa3b, v197
	v_add_f32_e32 v148, 1.0, v148
	v_rcp_f32_e32 v148, v148
	v_max_f32_e32 v0, 0xda24260, v0
	v_cvt_pk_bf16_f32 v147, v0, v147
	v_mul_f32_e32 v0, 0xbfb8aa3b, v198
	v_exp_f32_e32 v0, v0
	v_max_f32_e32 v148, 0xda24260, v148
	v_exp_f32_e32 v149, v149
	v_add_f32_e32 v0, 1.0, v0
	v_rcp_f32_e32 v0, v0
	v_add_f32_e32 v149, 1.0, v149
	v_rcp_f32_e32 v149, v149
	v_max_f32_e32 v0, 0xda24260, v0
	v_cvt_pk_bf16_f32 v148, v0, v148
	v_mul_f32_e32 v0, 0xbfb8aa3b, v196
	v_exp_f32_e32 v0, v0
	v_max_f32_e32 v149, 0xda24260, v149
	v_add_f32_e32 v0, 1.0, v0
	v_rcp_f32_e32 v0, v0
	s_nop 0
	v_max_f32_e32 v0, 0xda24260, v0
	v_cvt_pk_bf16_f32 v149, v0, v149
	global_store_dwordx4 v[194:195], v[146:149], off offset:256 nt
	s_nop 1
	v_mov_b32_e32 v0, v211
	v_pk_fma_f32 v[194:195], v[46:47], v[0:1], v[142:143] op_sel_hi:[1,0,1]
	v_pk_fma_f32 v[148:149], v[48:49], v[0:1], v[144:145] op_sel_hi:[1,0,1]
	v_pk_fma_f32 v[196:197], v[42:43], v[0:1], v[138:139] op_sel_hi:[1,0,1]
	v_mul_f32_e32 v148, 0xbfb8aa3b, v148
	v_mul_f32_e32 v149, 0xbfb8aa3b, v149
	v_exp_f32_e32 v148, v148
	v_exp_f32_e32 v149, v149
	v_mul_f32_e32 v163, 0xbfb8aa3b, v194
	v_mul_f32_e32 v194, 0xbfb8aa3b, v195
	v_add_f32_e32 v148, 1.0, v148
	v_add_f32_e32 v149, 1.0, v149
	v_rcp_f32_e32 v148, v148
	v_rcp_f32_e32 v149, v149
	v_pk_fma_f32 v[198:199], v[44:45], v[0:1], v[140:141] op_sel_hi:[1,0,1]
	v_exp_f32_e32 v163, v163
	v_max_f32_e32 v148, 0xda24260, v148
	v_max_f32_e32 v149, 0xda24260, v149
	v_cvt_pk_bf16_f32 v195, v148, v149
	v_mul_f32_e32 v148, 0xbfb8aa3b, v196
	v_mul_f32_e32 v149, 0xbfb8aa3b, v197
	v_exp_f32_e32 v148, v148
	v_exp_f32_e32 v149, v149
	v_exp_f32_e32 v194, v194
	v_add_f32_e32 v163, 1.0, v163
	v_add_f32_e32 v148, 1.0, v148
	v_add_f32_e32 v149, 1.0, v149
	v_rcp_f32_e32 v148, v148
	v_rcp_f32_e32 v149, v149
	v_add_f32_e32 v194, 1.0, v194
	v_rcp_f32_e32 v163, v163
	v_max_f32_e32 v148, 0xda24260, v148
	v_max_f32_e32 v149, 0xda24260, v149
	v_cvt_pk_bf16_f32 v196, v148, v149
	v_mul_f32_e32 v148, 0xbfb8aa3b, v198
	v_mul_f32_e32 v149, 0xbfb8aa3b, v199
	v_exp_f32_e32 v148, v148
	v_exp_f32_e32 v149, v149
	v_rcp_f32_e32 v194, v194
	v_max_f32_e32 v163, 0xda24260, v163
	v_add_f32_e32 v148, 1.0, v148
	v_add_f32_e32 v149, 1.0, v149
	v_rcp_f32_e32 v148, v148
	v_rcp_f32_e32 v149, v149
	v_max_f32_e32 v194, 0xda24260, v194
	v_cvt_pk_bf16_f32 v194, v163, v194
	v_max_f32_e32 v148, 0xda24260, v148
	v_max_f32_e32 v149, 0xda24260, v149
	v_cvt_pk_bf16_f32 v197, v148, v149
	v_add_co_u32_e32 v148, vcc, s11, v164
	v_pk_fma_f32 v[198:199], v[36:37], v[0:1], v[132:133] op_sel_hi:[1,0,1]
	s_nop 0
	v_addc_co_u32_e32 v149, vcc, 0, v165, vcc
	global_store_dwordx4 v[148:149], v[194:197], off nt
	v_pk_fma_f32 v[148:149], v[40:41], v[0:1], v[136:137] op_sel_hi:[1,0,1]
	v_lshl_add_u64 v[146:147], v[164:165], 0, s[20:21]
	v_pk_fma_f32 v[194:195], v[38:39], v[0:1], v[134:135] op_sel_hi:[1,0,1]
	v_pk_fma_f32 v[196:197], v[34:35], v[0:1], v[130:131] op_sel_hi:[1,0,1]
	v_mul_f32_e32 v0, 0xbfb8aa3b, v194
	v_mul_f32_e32 v163, 0xbfb8aa3b, v195
	v_exp_f32_e32 v0, v0
	v_exp_f32_e32 v163, v163
	s_mov_b32 s11, 0x50000
	s_mov_b64 s[20:21], 0x50000
	v_add_f32_e32 v0, 1.0, v0
	v_add_f32_e32 v163, 1.0, v163
	v_rcp_f32_e32 v0, v0
	v_rcp_f32_e32 v163, v163
	v_max_f32_e32 v0, 0xda24260, v0
	v_max_f32_e32 v163, 0xda24260, v163
	v_cvt_pk_bf16_f32 v194, v0, v163
	v_mul_f32_e32 v0, 0xbfb8aa3b, v148
	v_mul_f32_e32 v148, 0xbfb8aa3b, v149
	v_exp_f32_e32 v0, v0
	v_exp_f32_e32 v148, v148
	v_add_f32_e32 v0, 1.0, v0
	v_add_f32_e32 v148, 1.0, v148
	v_rcp_f32_e32 v0, v0
; #define GAS __attribute__((address_space(1)))
; __device__ __forceinline__ unsigned cvt_pk_bf16(float lo, float hi) { f32x2 v = {lo, hi}; bf16x2_t b = __builtin_convertvector(v, bf16x2_t); return __builtin_bit_cast(unsigned, b); }
; __device__ __forceinline__ float sigmoid_f(float x) { return __builtin_amdgcn_rcpf(1.0f + __builtin_amdgcn_exp2f(-x * LOG2E)); }
;     __device__ __forceinline__ void operator()(const f32x4 (&acc)[2][2][4][2], const Unit& u, int wr, int wc, int fr, int fq) const {
;     ...
;             for (int m = 0; m < 4; ++m) { const int row = row0 + ai * HALF + m * 16; const float rs = q.rs1[row]; GAS bf16_t* rowp = G + (size_t)row * 1024 + col0;
; #pragma unroll
;                 for (int bj = 0; bj < 2; ++bj) { const f32x4 v0 = acc[ai][bj][m][0] * rs + bv[bj][0], v1 = acc[ai][bj][m][1] * rs + bv[bj][1];
;                     u32x4 w; w.x = cvt_pk_bf16(fmaxf(sigmoid_f(v0[0]), 1e-30f), fmaxf(sigmoid_f(v0[1]), 1e-30f)); w.y = cvt_pk_bf16(fmaxf(sigmoid_f(v0[2]), 1e-30f), fmaxf(sigmoid_f(v0[3]), 1e-30f));
;                     w.z = cvt_pk_bf16(fmaxf(sigmoid_f(v1[0]), 1e-30f), fmaxf(sigmoid_f(v1[1]), 1e-30f)); w.w = cvt_pk_bf16(fmaxf(sigmoid_f(v1[2]), 1e-30f), fmaxf(sigmoid_f(v1[3]), 1e-30f));
;                     *(GAS u32x4*)(rowp + bj * HALF) = w; } }
	v_rcp_f32_e32 v148, v148
	v_max_f32_e32 v0, 0xda24260, v0
	v_max_f32_e32 v148, 0xda24260, v148
	v_cvt_pk_bf16_f32 v195, v0, v148
	v_mul_f32_e32 v0, 0xbfb8aa3b, v196
	v_mul_f32_e32 v148, 0xbfb8aa3b, v197
	v_exp_f32_e32 v0, v0
	v_exp_f32_e32 v148, v148
	v_add_f32_e32 v0, 1.0, v0
	v_add_f32_e32 v148, 1.0, v148
	v_rcp_f32_e32 v0, v0
	v_rcp_f32_e32 v148, v148
	v_max_f32_e32 v0, 0xda24260, v0
	v_max_f32_e32 v148, 0xda24260, v148
	v_cvt_pk_bf16_f32 v196, v0, v148
	v_mul_f32_e32 v0, 0xbfb8aa3b, v198
	v_mul_f32_e32 v148, 0xbfb8aa3b, v199
	v_exp_f32_e32 v0, v0
	v_exp_f32_e32 v148, v148
	v_add_f32_e32 v0, 1.0, v0
	v_add_f32_e32 v148, 1.0, v148
	v_rcp_f32_e32 v0, v0
	v_rcp_f32_e32 v148, v148
	v_max_f32_e32 v0, 0xda24260, v0
	v_max_f32_e32 v148, 0xda24260, v148
	v_cvt_pk_bf16_f32 v197, v0, v148
	global_store_dwordx4 v[146:147], v[194:197], off offset:256 nt
	v_lshl_add_u64 v[146:147], v[164:165], 0, s[20:21]
	s_mov_b64 s[20:21], 0x58000
	s_nop 1
	v_mov_b32_e32 v0, v212
	v_pk_fma_f32 v[148:149], v[32:33], v[0:1], v[144:145] op_sel_hi:[1,0,1]
	s_nop 0
	v_mul_f32_e32 v148, 0xbfb8aa3b, v148
	v_mul_f32_e32 v149, 0xbfb8aa3b, v149
	v_exp_f32_e32 v148, v148
	v_exp_f32_e32 v149, v149
	v_pk_fma_f32 v[194:195], v[30:31], v[0:1], v[142:143] op_sel_hi:[1,0,1]
	v_pk_fma_f32 v[196:197], v[26:27], v[0:1], v[138:139] op_sel_hi:[1,0,1]
	v_add_f32_e32 v148, 1.0, v148
	v_add_f32_e32 v149, 1.0, v149
	v_rcp_f32_e32 v148, v148
	v_rcp_f32_e32 v149, v149
	v_mul_f32_e32 v163, 0xbfb8aa3b, v194
	v_mul_f32_e32 v194, 0xbfb8aa3b, v195
	v_max_f32_e32 v148, 0xda24260, v148
	v_max_f32_e32 v149, 0xda24260, v149
	v_cvt_pk_bf16_f32 v195, v148, v149
	v_mul_f32_e32 v148, 0xbfb8aa3b, v196
	v_mul_f32_e32 v149, 0xbfb8aa3b, v197
	v_exp_f32_e32 v148, v148
	v_exp_f32_e32 v149, v149
	v_pk_fma_f32 v[198:199], v[28:29], v[0:1], v[140:141] op_sel_hi:[1,0,1]
	v_exp_f32_e32 v163, v163
	v_add_f32_e32 v148, 1.0, v148
	v_add_f32_e32 v149, 1.0, v149
	v_rcp_f32_e32 v148, v148
	v_rcp_f32_e32 v149, v149
	v_exp_f32_e32 v194, v194
	v_add_f32_e32 v163, 1.0, v163
	v_max_f32_e32 v148, 0xda24260, v148
	v_max_f32_e32 v149, 0xda24260, v149
	v_cvt_pk_bf16_f32 v196, v148, v149
	v_mul_f32_e32 v148, 0xbfb8aa3b, v198
	v_mul_f32_e32 v149, 0xbfb8aa3b, v199
	v_exp_f32_e32 v148, v148
	v_exp_f32_e32 v149, v149
	v_add_f32_e32 v194, 1.0, v194
	v_rcp_f32_e32 v163, v163
	v_add_f32_e32 v148, 1.0, v148
	v_add_f32_e32 v149, 1.0, v149
	v_rcp_f32_e32 v148, v148
	v_rcp_f32_e32 v149, v149
	v_rcp_f32_e32 v194, v194
	v_max_f32_e32 v163, 0xda24260, v163
	v_max_f32_e32 v148, 0xda24260, v148
	v_max_f32_e32 v149, 0xda24260, v149
	v_max_f32_e32 v194, 0xda24260, v194
	v_cvt_pk_bf16_f32 v197, v148, v149
	v_add_co_u32_e32 v148, vcc, s11, v164
	v_cvt_pk_bf16_f32 v194, v163, v194
	s_nop 0
	v_addc_co_u32_e32 v149, vcc, 0, v165, vcc
	global_store_dwordx4 v[148:149], v[194:197], off nt
	v_pk_fma_f32 v[148:149], v[24:25], v[0:1], v[136:137] op_sel_hi:[1,0,1]
	v_pk_fma_f32 v[198:199], v[20:21], v[0:1], v[132:133] op_sel_hi:[1,0,1]
	v_pk_fma_f32 v[194:195], v[22:23], v[0:1], v[134:135] op_sel_hi:[1,0,1]
	v_pk_fma_f32 v[196:197], v[18:19], v[0:1], v[130:131] op_sel_hi:[1,0,1]
	v_mul_f32_e32 v0, 0xbfb8aa3b, v194
	v_mul_f32_e32 v163, 0xbfb8aa3b, v195
	v_exp_f32_e32 v0, v0
	v_exp_f32_e32 v163, v163
	s_mov_b32 s11, 0x58000
	v_add_f32_e32 v0, 1.0, v0
	v_add_f32_e32 v163, 1.0, v163
	v_rcp_f32_e32 v0, v0
	v_rcp_f32_e32 v163, v163
	v_max_f32_e32 v0, 0xda24260, v0
	v_max_f32_e32 v163, 0xda24260, v163
	v_cvt_pk_bf16_f32 v194, v0, v163
	v_mul_f32_e32 v0, 0xbfb8aa3b, v148
	v_mul_f32_e32 v148, 0xbfb8aa3b, v149
	v_exp_f32_e32 v0, v0
	v_exp_f32_e32 v148, v148
	v_add_f32_e32 v0, 1.0, v0
	v_add_f32_e32 v148, 1.0, v148
	v_rcp_f32_e32 v0, v0
	v_rcp_f32_e32 v148, v148
	v_max_f32_e32 v0, 0xda24260, v0
	v_max_f32_e32 v148, 0xda24260, v148
	v_cvt_pk_bf16_f32 v195, v0, v148
	v_mul_f32_e32 v0, 0xbfb8aa3b, v196
	v_mul_f32_e32 v148, 0xbfb8aa3b, v197
	v_exp_f32_e32 v0, v0
	v_exp_f32_e32 v148, v148
	v_add_f32_e32 v0, 1.0, v0
	v_add_f32_e32 v148, 1.0, v148
	v_rcp_f32_e32 v0, v0
	v_rcp_f32_e32 v148, v148
	v_max_f32_e32 v0, 0xda24260, v0
	v_max_f32_e32 v148, 0xda24260, v148
; #define GAS __attribute__((address_space(1)))
; __device__ __forceinline__ unsigned cvt_pk_bf16(float lo, float hi) { f32x2 v = {lo, hi}; bf16x2_t b = __builtin_convertvector(v, bf16x2_t); return __builtin_bit_cast(unsigned, b); }
; __device__ __forceinline__ float sigmoid_f(float x) { return __builtin_amdgcn_rcpf(1.0f + __builtin_amdgcn_exp2f(-x * LOG2E)); }
;     __device__ __forceinline__ void operator()(const f32x4 (&acc)[2][2][4][2], const Unit& u, int wr, int wc, int fr, int fq) const {
;     ...
;             for (int m = 0; m < 4; ++m) { const int row = row0 + ai * HALF + m * 16; const float rs = q.rs1[row]; GAS bf16_t* rowp = G + (size_t)row * 1024 + col0;
; #pragma unroll
;                 for (int bj = 0; bj < 2; ++bj) { const f32x4 v0 = acc[ai][bj][m][0] * rs + bv[bj][0], v1 = acc[ai][bj][m][1] * rs + bv[bj][1];
;                     u32x4 w; w.x = cvt_pk_bf16(fmaxf(sigmoid_f(v0[0]), 1e-30f), fmaxf(sigmoid_f(v0[1]), 1e-30f)); w.y = cvt_pk_bf16(fmaxf(sigmoid_f(v0[2]), 1e-30f), fmaxf(sigmoid_f(v0[3]), 1e-30f));
;                     w.z = cvt_pk_bf16(fmaxf(sigmoid_f(v1[0]), 1e-30f), fmaxf(sigmoid_f(v1[1]), 1e-30f)); w.w = cvt_pk_bf16(fmaxf(sigmoid_f(v1[2]), 1e-30f), fmaxf(sigmoid_f(v1[3]), 1e-30f));
;                     *(GAS u32x4*)(rowp + bj * HALF) = w; } }
	v_cvt_pk_bf16_f32 v196, v0, v148
	v_mul_f32_e32 v0, 0xbfb8aa3b, v198
	v_mul_f32_e32 v148, 0xbfb8aa3b, v199
	v_exp_f32_e32 v0, v0
	v_exp_f32_e32 v148, v148
	v_add_f32_e32 v0, 1.0, v0
	v_add_f32_e32 v148, 1.0, v148
	v_rcp_f32_e32 v0, v0
	v_rcp_f32_e32 v148, v148
	v_max_f32_e32 v0, 0xda24260, v0
	v_max_f32_e32 v148, 0xda24260, v148
	v_cvt_pk_bf16_f32 v197, v0, v148
	global_store_dwordx4 v[146:147], v[194:197], off offset:256 nt
	v_lshl_add_u64 v[146:147], v[164:165], 0, s[20:21]
	s_nop 1
	v_mov_b32_e32 v0, v213
	v_pk_fma_f32 v[142:143], v[14:15], v[0:1], v[142:143] op_sel_hi:[1,0,1]
	v_pk_fma_f32 v[148:149], v[12:13], v[0:1], v[140:141] op_sel_hi:[1,0,1]
	v_pk_fma_f32 v[140:141], v[10:11], v[0:1], v[138:139] op_sel_hi:[1,0,1]
	v_mul_f32_e32 v138, 0xbfb8aa3b, v142
	v_mul_f32_e32 v139, 0xbfb8aa3b, v143
	v_exp_f32_e32 v138, v138
	v_exp_f32_e32 v139, v139
	v_pk_fma_f32 v[144:145], v[16:17], v[0:1], v[144:145] op_sel_hi:[1,0,1]
	v_mul_f32_e32 v140, 0xbfb8aa3b, v140
	v_add_f32_e32 v138, 1.0, v138
	v_add_f32_e32 v139, 1.0, v139
	v_rcp_f32_e32 v138, v138
	v_rcp_f32_e32 v139, v139
	v_mul_f32_e32 v142, 0xbfb8aa3b, v145
	v_mul_f32_e32 v141, 0xbfb8aa3b, v141
	v_max_f32_e32 v138, 0xda24260, v138
	v_max_f32_e32 v139, 0xda24260, v139
	v_cvt_pk_bf16_f32 v138, v138, v139
	v_mul_f32_e32 v139, 0xbfb8aa3b, v144
	v_exp_f32_e32 v139, v139
	v_exp_f32_e32 v142, v142
	v_exp_f32_e32 v140, v140
	v_exp_f32_e32 v141, v141
	v_add_f32_e32 v139, 1.0, v139
	v_add_f32_e32 v142, 1.0, v142
	v_add_f32_e32 v140, 1.0, v140
	v_add_f32_e32 v141, 1.0, v141
	v_rcp_f32_e32 v139, v139
	v_rcp_f32_e32 v142, v142
	v_rcp_f32_e32 v140, v140
	v_rcp_f32_e32 v141, v141
	v_max_f32_e32 v139, 0xda24260, v139
	v_max_f32_e32 v142, 0xda24260, v142
	v_max_f32_e32 v140, 0xda24260, v140
	v_max_f32_e32 v141, 0xda24260, v141
	v_cvt_pk_bf16_f32 v139, v139, v142
	v_cvt_pk_bf16_f32 v140, v140, v141
	v_mul_f32_e32 v141, 0xbfb8aa3b, v148
	v_mul_f32_e32 v142, 0xbfb8aa3b, v149
	v_exp_f32_e32 v141, v141
	v_exp_f32_e32 v142, v142
	v_pk_fma_f32 v[134:135], v[6:7], v[0:1], v[134:135] op_sel_hi:[1,0,1]
	v_pk_fma_f32 v[136:137], v[8:9], v[0:1], v[136:137] op_sel_hi:[1,0,1]
	v_add_f32_e32 v141, 1.0, v141
	v_add_f32_e32 v142, 1.0, v142
	v_rcp_f32_e32 v141, v141
	v_rcp_f32_e32 v142, v142
	v_max_f32_e32 v141, 0xda24260, v141
	v_max_f32_e32 v142, 0xda24260, v142
	v_cvt_pk_bf16_f32 v141, v141, v142
	v_add_co_u32_e32 v142, vcc, s11, v164
	s_nop 1
	v_addc_co_u32_e32 v143, vcc, 0, v165, vcc
	global_store_dwordx4 v[142:143], v[138:141], off nt
	s_nop 1
	v_pk_fma_f32 v[138:139], v[4:5], v[0:1], v[132:133] op_sel_hi:[1,0,1]
	v_pk_fma_f32 v[132:133], v[2:3], v[0:1], v[130:131] op_sel_hi:[1,0,1]
	v_mul_f32_e32 v0, 0xbfb8aa3b, v134
	v_mul_f32_e32 v130, 0xbfb8aa3b, v135
	v_exp_f32_e32 v0, v0
	v_exp_f32_e32 v130, v130
	v_mul_f32_e32 v131, 0xbfb8aa3b, v137
	v_exp_f32_e32 v131, v131
	v_add_f32_e32 v0, 1.0, v0
	v_add_f32_e32 v130, 1.0, v130
	v_rcp_f32_e32 v0, v0
	v_rcp_f32_e32 v130, v130
	v_add_f32_e32 v131, 1.0, v131
	v_rcp_f32_e32 v131, v131
	v_max_f32_e32 v0, 0xda24260, v0
	v_max_f32_e32 v130, 0xda24260, v130
	v_cvt_pk_bf16_f32 v130, v0, v130
	v_mul_f32_e32 v0, 0xbfb8aa3b, v136
	v_exp_f32_e32 v0, v0
	v_max_f32_e32 v131, 0xda24260, v131
	v_add_f32_e32 v0, 1.0, v0
	v_rcp_f32_e32 v0, v0
	s_nop 0
	v_max_f32_e32 v0, 0xda24260, v0
	v_cvt_pk_bf16_f32 v131, v0, v131
	v_mul_f32_e32 v0, 0xbfb8aa3b, v132
	v_mul_f32_e32 v132, 0xbfb8aa3b, v133
	v_exp_f32_e32 v0, v0
	v_exp_f32_e32 v132, v132
	v_mul_f32_e32 v133, 0xbfb8aa3b, v139
	v_exp_f32_e32 v133, v133
	v_add_f32_e32 v0, 1.0, v0
	v_add_f32_e32 v132, 1.0, v132
	v_rcp_f32_e32 v0, v0
	v_rcp_f32_e32 v132, v132
	v_add_f32_e32 v133, 1.0, v133
	v_rcp_f32_e32 v133, v133
	v_max_f32_e32 v0, 0xda24260, v0
	v_max_f32_e32 v132, 0xda24260, v132
	v_cvt_pk_bf16_f32 v132, v0, v132
	v_mul_f32_e32 v0, 0xbfb8aa3b, v138
	v_exp_f32_e32 v0, v0
	v_max_f32_e32 v133, 0xda24260, v133
	v_add_f32_e32 v0, 1.0, v0
	v_rcp_f32_e32 v0, v0
	s_nop 0
	v_max_f32_e32 v0, 0xda24260, v0
	v_cvt_pk_bf16_f32 v133, v0, v133
	global_store_dwordx4 v[146:147], v[130:133], off offset:256 nt
	s_cbranch_execnz .LBB0_250
